# N3: per-layer norm+modulation loads its 8 norm-weight quads once before the row loop instead of per row (on top of C6)
# speedup vs baseline: 1.0141x; 1.0032x over previous
.LBB0_388:
	s_and_b64 vcc, exec, s[54:55]
	s_cbranch_vccz .LBB0_422
	s_waitcnt vmcnt(0)
	v_mbcnt_lo_u32_b32 v2, -1, 0
	v_mbcnt_hi_u32_b32 v2, -1, v2
	v_readlane_b32 s0, v254, 24
	v_add_u32_e32 v0, s87, v2
	v_ashrrev_i32_e32 v0, 6, v0
	v_add_u32_e32 v159, s0, v0
	s_movk_i32 s0, 0x3000
	v_cmp_gt_i32_e32 vcc, s0, v159
	v_readlane_b32 s1, v254, 25
	s_and_saveexec_b64 s[2:3], vcc
	v_readlane_b32 s6, v254, 60
	v_readlane_b32 s7, v254, 61
	v_readlane_b32 s8, v254, 53
	v_readlane_b32 s10, v255, 4
	v_readlane_b32 s16, v255, 6
	v_readlane_b32 s26, v255, 10
	s_movk_i32 s7, 0x2fff
	v_readlane_b32 s9, v254, 54
	v_readlane_b32 s11, v255, 5
	v_readlane_b32 s17, v255, 7
	v_readlane_b32 s27, v255, 11
	s_cbranch_execz .LBB0_392
	v_readlane_b32 s48, v251, 3
	v_readlane_b32 s0, v255, 8
	v_readlane_b32 s49, v251, 4
	v_readlane_b32 s50, v251, 5
	v_readlane_b32 s51, v251, 6
	v_readlane_b32 s52, v251, 7
	v_readlane_b32 s53, v251, 8
	v_readlane_b32 s54, v251, 9
	v_readlane_b32 s55, v251, 10
	v_readlane_b32 s56, v251, 11
	v_readlane_b32 s57, v251, 12
	v_readlane_b32 s58, v251, 13
	v_readlane_b32 s59, v251, 14
	v_readlane_b32 s1, v255, 9
	v_readlane_b32 s60, v251, 15
	v_readlane_b32 s61, v251, 16
	v_readlane_b32 s62, v251, 17
	v_readlane_b32 s63, v251, 18
	s_mov_b64 s[48:49], s[52:53]
	s_lshl_b64 s[0:1], s[0:1], 13
	s_mov_b64 s[50:51], s[54:55]
	s_mov_b64 s[52:53], s[56:57]
	s_mov_b64 s[54:55], s[58:59]
	v_lshlrev_b32_e32 v1, 2, v2
	s_add_u32 s0, s54, s0
	v_and_b32_e32 v4, 0xfc, v1
	s_addc_u32 s1, s55, s1
	v_lshlrev_b32_e32 v128, 2, v4
	v_or_b32_e32 v12, 0x400, v4
	v_lshl_add_u64 v[130:131], s[0:1], 0, v[128:129]
	v_lshlrev_b32_e32 v128, 2, v12
	v_or_b32_e32 v14, 0x500, v4
	v_lshl_add_u64 v[132:133], s[0:1], 0, v[128:129]
	v_lshlrev_b32_e32 v128, 2, v14
	v_or_b32_e32 v16, 0x600, v4
	v_lshl_add_u64 v[134:135], s[0:1], 0, v[128:129]
	v_lshlrev_b32_e32 v128, 2, v16
	v_or_b32_e32 v18, 0x700, v4
	v_lshl_add_u64 v[136:137], s[0:1], 0, v[128:129]
	v_lshlrev_b32_e32 v128, 2, v18
	s_movk_i32 s4, 0x80
	v_lshl_add_u64 v[138:139], s[0:1], 0, v[128:129]
	v_readlane_b32 s0, v254, 24
	v_bitop3_b32 v160, v1, s4, v242 bitop3:0x6c
	v_bitop3_b32 v161, v1, 64, v242 bitop3:0x6c
	v_bitop3_b32 v162, v1, 32, v242 bitop3:0x6c
	v_bitop3_b32 v163, v1, 16, v242 bitop3:0x6c
	v_bitop3_b32 v164, v1, 8, v242 bitop3:0x6c
	v_bitop3_b32 v165, v1, 4, v242 bitop3:0x6c
	v_ashrrev_i32_e32 v1, 31, v0
	v_readlane_b32 s1, v254, 25
	v_and_b32_e32 v2, 63, v2
	v_or_b32_e32 v6, 0x100, v4
	v_lshl_add_u64 v[0:1], s[0:1], 0, v[0:1]
	v_lshlrev_b64 v[140:141], 13, v[0:1]
	v_lshlrev_b64 v[0:1], 12, v[0:1]
	v_readlane_b32 s0, v254, 27
	v_or_b32_e32 v8, 0x200, v4
	v_or_b32_e32 v10, 0x300, v4
	v_lshlrev_b32_e32 v3, 4, v2
	v_lshl_or_b32 v0, v2, 3, v0
	v_readlane_b32 s1, v254, 28
	v_or3_b32 v140, v140, v3, s85
	s_mov_b64 s[4:5], 0
	v_lshl_add_u64 v[142:143], s[0:1], 0, v[0:1]
	v_lshlrev_b32_e32 v128, 2, v4
	v_lshlrev_b32_e32 v144, 2, v6
	v_lshlrev_b32_e32 v146, 2, v8
	v_lshlrev_b32_e32 v148, 2, v10
	v_lshlrev_b32_e32 v150, 2, v12
	v_lshlrev_b32_e32 v152, 2, v14
	v_lshlrev_b32_e32 v154, 2, v16
	v_lshlrev_b32_e32 v156, 2, v18
	s_mov_b64 s[56:57], s[60:61]
	s_mov_b64 s[58:59], s[62:63]
	global_load_dwordx4 v[170:173], v[130:131], off
	global_load_dwordx4 v[174:177], v[130:131], off offset:1024
	global_load_dwordx4 v[178:181], v[130:131], off offset:2048
	global_load_dwordx4 v[182:185], v[130:131], off offset:3072
	global_load_dwordx4 v[186:189], v[132:133], off
	global_load_dwordx4 v[190:193], v[134:135], off
	global_load_dwordx4 v[194:197], v[136:137], off
	global_load_dwordx4 v[198:201], v[138:139], off
.LBB0_391:
	v_mov_b32_e32 v0, s17
	v_mov_b32_e32 v1, s11
	v_cmp_gt_i32_e32 vcc, s85, v159
	v_mov_b32_e32 v2, s10
	v_mov_b32_e32 v145, v129
	v_cndmask_b32_e32 v1, v0, v1, vcc
	v_mov_b32_e32 v0, s16
	v_cndmask_b32_e32 v0, v0, v2, vcc
	v_add_u32_e32 v2, 0xfffff000, v159
	v_ashrrev_i32_e32 v2, 11, v2
	v_add_u32_e32 v2, 1, v2
	v_cndmask_b32_e64 v2, v2, 0, vcc
	v_mul_hi_i32_i24_e32 v3, 0x6000, v2
	v_mul_i32_i24_e32 v2, 0x6000, v2
	v_lshl_add_u64 v[2:3], s[26:27], 0, v[2:3]
	v_lshl_add_u64 v[4:5], v[2:3], 0, s[20:21]
	v_lshl_add_u64 v[6:7], v[4:5], 0, v[128:129]
	v_mov_b32_e32 v147, v129
	v_lshl_add_u64 v[0:1], v[0:1], 0, v[140:141]
	v_lshl_add_u64 v[8:9], v[2:3], 0, v[128:129]
	global_load_dwordx4 v[112:115], v[6:7], off
	global_load_dwordx4 v[116:119], v[8:9], off
	global_load_dwordx4 v[120:123], v[0:1], off offset:-4096
	global_load_dwordx4 v[100:103], v[0:1], off offset:-3072
	v_lshl_add_u64 v[6:7], v[4:5], 0, v[144:145]
	v_lshl_add_u64 v[10:11], v[4:5], 0, v[146:147]
	v_mov_b32_e32 v149, v129
	v_mov_b32_e32 v151, v129
	global_load_dwordx4 v[96:99], v[8:9], off offset:1024
	global_load_dwordx4 v[80:83], v[8:9], off offset:2048
	global_load_dwordx4 v[88:91], v[0:1], off offset:-2048
	global_load_dwordx4 v[72:75], v[0:1], off offset:-1024
	v_lshl_add_u64 v[12:13], v[4:5], 0, v[148:149]
	global_load_dwordx4 v[84:87], v[10:11], off
	global_load_dwordx4 v[64:67], v[12:13], off
	global_load_dwordx4 v[108:111], v[6:7], off
	global_load_dwordx4 v[68:71], v[8:9], off offset:3072
	v_lshl_add_u64 v[6:7], v[4:5], 0, v[150:151]
	v_lshl_add_u64 v[8:9], v[2:3], 0, v[150:151]
	v_mov_b32_e32 v153, v129
	global_load_dwordx4 v[48:51], v[6:7], off
	global_load_dwordx4 v[52:55], v[8:9], off
	global_load_dwordx4 v[56:59], v[0:1], off
	global_load_dwordx4 v[40:43], v[0:1], off offset:1024
	v_lshl_add_u64 v[6:7], v[4:5], 0, v[152:153]
	v_lshl_add_u64 v[8:9], v[2:3], 0, v[152:153]
	v_mov_b32_e32 v155, v129
	global_load_dwordx4 v[32:35], v[6:7], off
	global_load_dwordx4 v[36:39], v[8:9], off
	v_lshl_add_u64 v[6:7], v[4:5], 0, v[154:155]
	v_lshl_add_u64 v[8:9], v[2:3], 0, v[154:155]
	global_load_dwordx4 v[16:19], v[6:7], off
	global_load_dwordx4 v[20:23], v[8:9], off
	global_load_dwordx4 v[24:27], v[0:1], off offset:2048
	s_nop 0
	global_load_dwordx4 v[8:11], v[0:1], off offset:3072
	v_mov_b32_e32 v157, v129
	v_lshl_add_u64 v[0:1], v[4:5], 0, v[156:157]
	v_lshl_add_u64 v[4:5], v[2:3], 0, v[156:157]
	global_load_dwordx4 v[0:3], v[0:1], off
	s_nop 0
	global_load_dwordx4 v[4:7], v[4:5], off
	s_waitcnt vmcnt(0)
	v_mov_b64_e32 v[124:125], v[170:171]
	v_mov_b64_e32 v[126:127], v[172:173]
	v_mov_b64_e32 v[104:105], v[174:175]
	v_mov_b64_e32 v[106:107], v[176:177]
	v_mov_b64_e32 v[92:93], v[178:179]
	v_mov_b64_e32 v[94:95], v[180:181]
	v_mov_b64_e32 v[76:77], v[182:183]
	v_mov_b64_e32 v[78:79], v[184:185]
	v_mov_b64_e32 v[60:61], v[186:187]
	v_mov_b64_e32 v[62:63], v[188:189]
	v_mov_b64_e32 v[44:45], v[190:191]
	v_mov_b64_e32 v[46:47], v[192:193]
	v_mov_b64_e32 v[28:29], v[194:195]
	v_mov_b64_e32 v[30:31], v[196:197]
	v_mov_b64_e32 v[12:13], v[198:199]
	v_mov_b64_e32 v[14:15], v[200:201]
	v_mul_f32_e32 v145, v121, v121
	v_mul_f32_e32 v147, v101, v101
	v_fmac_f32_e32 v145, v120, v120
	v_fmac_f32_e32 v147, v100, v100
	v_fmac_f32_e32 v145, v122, v122
	v_fmac_f32_e32 v147, v102, v102
	v_fmac_f32_e32 v145, v123, v123
	v_fmac_f32_e32 v147, v103, v103
	v_add_f32_e32 v145, v145, v147
	v_mul_f32_e32 v147, v89, v89
	v_fmac_f32_e32 v147, v88, v88
	v_fmac_f32_e32 v147, v90, v90
	v_fmac_f32_e32 v147, v91, v91
	v_add_f32_e32 v145, v145, v147
	v_mul_f32_e32 v147, v73, v73
	v_mov_b32_e32 v168, v57
	v_mov_b32_e32 v169, v41
	v_fmac_f32_e32 v147, v72, v72
	v_mov_b32_e32 v166, v56
	v_mov_b32_e32 v167, v40
	v_pk_mul_f32 v[168:169], v[168:169], v[168:169]
	v_fmac_f32_e32 v147, v74, v74
	v_pk_fma_f32 v[166:167], v[166:167], v[166:167], v[168:169]
	v_mov_b32_e32 v168, v58
	v_mov_b32_e32 v169, v42
	v_fmac_f32_e32 v147, v75, v75
	v_pk_fma_f32 v[166:167], v[168:169], v[168:169], v[166:167]
	v_mov_b32_e32 v168, v59
	v_mov_b32_e32 v169, v43
	v_add_f32_e32 v145, v145, v147
	v_pk_fma_f32 v[166:167], v[168:169], v[168:169], v[166:167]
	v_mov_b32_e32 v168, v25
	v_add_f32_e32 v145, v145, v166
	v_mov_b32_e32 v169, v9
	v_add_f32_e32 v145, v145, v167
	v_mov_b32_e32 v166, v24
	v_mov_b32_e32 v167, v8
	v_pk_mul_f32 v[168:169], v[168:169], v[168:169]
	v_pk_add_f32 v[112:113], v[112:113], 1.0 op_sel_hi:[1,0]
	v_pk_fma_f32 v[166:167], v[166:167], v[166:167], v[168:169]
	v_mov_b32_e32 v168, v26
	v_mov_b32_e32 v169, v10
	v_pk_fma_f32 v[166:167], v[168:169], v[168:169], v[166:167]
	v_mov_b32_e32 v168, v27
	v_mov_b32_e32 v169, v11
	v_pk_fma_f32 v[166:167], v[168:169], v[168:169], v[166:167]
	v_pk_add_f32 v[84:85], v[84:85], 1.0 op_sel_hi:[1,0]
	v_add_f32_e32 v145, v145, v166
	v_add_f32_e32 v145, v145, v167
	ds_bpermute_b32 v147, v160, v145
	v_pk_add_f32 v[64:65], v[64:65], 1.0 op_sel_hi:[1,0]
	v_pk_add_f32 v[48:49], v[48:49], 1.0 op_sel_hi:[1,0]
	v_pk_add_f32 v[32:33], v[32:33], 1.0 op_sel_hi:[1,0]
	v_pk_add_f32 v[16:17], v[16:17], 1.0 op_sel_hi:[1,0]
	s_waitcnt lgkmcnt(0)
	v_add_f32_e32 v145, v145, v147
	ds_bpermute_b32 v147, v161, v145
	v_pk_add_f32 v[0:1], v[0:1], 1.0 op_sel_hi:[1,0]
	v_pk_add_f32 v[114:115], v[114:115], 1.0 op_sel_hi:[1,0]
	v_pk_add_f32 v[86:87], v[86:87], 1.0 op_sel_hi:[1,0]
	v_pk_add_f32 v[66:67], v[66:67], 1.0 op_sel_hi:[1,0]
	s_waitcnt lgkmcnt(0)
	v_add_f32_e32 v145, v145, v147
	ds_bpermute_b32 v147, v162, v145
	v_pk_add_f32 v[50:51], v[50:51], 1.0 op_sel_hi:[1,0]
	v_pk_add_f32 v[34:35], v[34:35], 1.0 op_sel_hi:[1,0]
	v_pk_add_f32 v[18:19], v[18:19], 1.0 op_sel_hi:[1,0]
	v_pk_add_f32 v[2:3], v[2:3], 1.0 op_sel_hi:[1,0]
	s_waitcnt lgkmcnt(0)
	v_add_f32_e32 v145, v145, v147
	ds_bpermute_b32 v147, v163, v145
	v_lshl_add_u64 v[140:141], v[140:141], 0, s[18:19]
	s_waitcnt lgkmcnt(0)
	v_add_f32_e32 v145, v145, v147
	ds_bpermute_b32 v147, v164, v145
	s_waitcnt lgkmcnt(0)
	v_add_f32_e32 v145, v145, v147
	ds_bpermute_b32 v147, v165, v145
	s_waitcnt lgkmcnt(0)
	v_add_f32_e32 v145, v145, v147
	v_fmamk_f32 v145, v145, 0x3a000000, v234
	v_cmp_gt_f32_e32 vcc, s25, v145
	v_mul_f32_e32 v147, 0x4b800000, v145
	s_nop 0
	v_cndmask_b32_e32 v145, v145, v147, vcc
	v_rsq_f32_e32 v145, v145
	s_nop 0
	v_mul_f32_e32 v147, 0x45800000, v145
	v_cndmask_b32_e32 v158, v145, v147, vcc
	v_pk_mul_f32 v[120:121], v[120:121], v[158:159] op_sel_hi:[1,0]
	v_pk_mul_f32 v[100:101], v[100:101], v[158:159] op_sel_hi:[1,0]
	v_pk_mul_f32 v[88:89], v[88:89], v[158:159] op_sel_hi:[1,0]
	v_pk_mul_f32 v[72:73], v[72:73], v[158:159] op_sel_hi:[1,0]
	v_pk_mul_f32 v[56:57], v[56:57], v[158:159] op_sel_hi:[1,0]
	v_pk_mul_f32 v[40:41], v[40:41], v[158:159] op_sel_hi:[1,0]
	v_pk_mul_f32 v[24:25], v[24:25], v[158:159] op_sel_hi:[1,0]
	v_pk_mul_f32 v[8:9], v[8:9], v[158:159] op_sel_hi:[1,0]
	v_pk_mul_f32 v[120:121], v[124:125], v[120:121]
	v_pk_mul_f32 v[100:101], v[104:105], v[100:101]
	v_pk_add_f32 v[104:105], v[108:109], 1.0 op_sel_hi:[1,0]
	v_pk_mul_f32 v[88:89], v[92:93], v[88:89]
	v_pk_mul_f32 v[72:73], v[76:77], v[72:73]
	v_pk_mul_f32 v[56:57], v[60:61], v[56:57]
	v_pk_mul_f32 v[40:41], v[44:45], v[40:41]
	v_pk_mul_f32 v[24:25], v[28:29], v[24:25]
	v_pk_mul_f32 v[8:9], v[12:13], v[8:9]
	v_pk_fma_f32 v[112:113], v[112:113], v[120:121], v[116:117]
	v_pk_mul_f32 v[116:117], v[122:123], v[158:159] op_sel_hi:[1,0]
	v_pk_fma_f32 v[96:97], v[104:105], v[100:101], v[96:97]
	v_pk_mul_f32 v[100:101], v[102:103], v[158:159] op_sel_hi:[1,0]
	v_pk_fma_f32 v[80:81], v[84:85], v[88:89], v[80:81]
	v_pk_mul_f32 v[84:85], v[90:91], v[158:159] op_sel_hi:[1,0]
	v_pk_fma_f32 v[64:65], v[64:65], v[72:73], v[68:69]
	v_pk_mul_f32 v[68:69], v[74:75], v[158:159] op_sel_hi:[1,0]
	v_pk_fma_f32 v[48:49], v[48:49], v[56:57], v[52:53]
	v_pk_mul_f32 v[52:53], v[58:59], v[158:159] op_sel_hi:[1,0]
	v_pk_fma_f32 v[32:33], v[32:33], v[40:41], v[36:37]
	v_pk_mul_f32 v[36:37], v[42:43], v[158:159] op_sel_hi:[1,0]
	v_pk_fma_f32 v[16:17], v[16:17], v[24:25], v[20:21]
	v_pk_mul_f32 v[20:21], v[26:27], v[158:159] op_sel_hi:[1,0]
	v_pk_fma_f32 v[0:1], v[0:1], v[8:9], v[4:5]
	v_pk_mul_f32 v[4:5], v[10:11], v[158:159] op_sel_hi:[1,0]
	v_pk_mul_f32 v[116:117], v[126:127], v[116:117]
	v_pk_mul_f32 v[100:101], v[106:107], v[100:101]
	v_pk_add_f32 v[102:103], v[110:111], 1.0 op_sel_hi:[1,0]
	v_pk_mul_f32 v[84:85], v[94:95], v[84:85]
	v_pk_mul_f32 v[68:69], v[78:79], v[68:69]
	v_pk_mul_f32 v[52:53], v[62:63], v[52:53]
	v_pk_mul_f32 v[36:37], v[46:47], v[36:37]
	v_pk_mul_f32 v[20:21], v[30:31], v[20:21]
	v_pk_mul_f32 v[4:5], v[14:15], v[4:5]
	v_pk_fma_f32 v[114:115], v[114:115], v[116:117], v[118:119]
	v_pk_fma_f32 v[98:99], v[102:103], v[100:101], v[98:99]
	v_pk_fma_f32 v[82:83], v[86:87], v[84:85], v[82:83]
	v_pk_fma_f32 v[66:67], v[66:67], v[68:69], v[70:71]
	v_pk_fma_f32 v[50:51], v[50:51], v[52:53], v[54:55]
	v_pk_fma_f32 v[34:35], v[34:35], v[36:37], v[38:39]
	v_pk_fma_f32 v[18:19], v[18:19], v[20:21], v[22:23]
	v_pk_fma_f32 v[2:3], v[2:3], v[4:5], v[6:7]
	v_add_u32_e32 v159, s6, v159
	v_cvt_pk_bf16_f32 v112, v112, v113
	v_cvt_pk_bf16_f32 v113, v114, v115
	v_cvt_pk_bf16_f32 v96, v96, v97
	v_cvt_pk_bf16_f32 v97, v98, v99
	v_cvt_pk_bf16_f32 v80, v80, v81
	v_cvt_pk_bf16_f32 v81, v82, v83
	v_cvt_pk_bf16_f32 v64, v64, v65
	v_cvt_pk_bf16_f32 v65, v66, v67
	v_cvt_pk_bf16_f32 v48, v48, v49
	v_cvt_pk_bf16_f32 v49, v50, v51
	v_cvt_pk_bf16_f32 v32, v32, v33
	v_cvt_pk_bf16_f32 v33, v34, v35
	v_cvt_pk_bf16_f32 v16, v16, v17
	v_cvt_pk_bf16_f32 v17, v18, v19
	v_cvt_pk_bf16_f32 v0, v0, v1
	v_cvt_pk_bf16_f32 v1, v2, v3
	v_cmp_lt_i32_e32 vcc, s7, v159
	global_store_dwordx2 v[142:143], v[112:113], off offset:-2048
	global_store_dwordx2 v[142:143], v[96:97], off offset:-1536
	global_store_dwordx2 v[142:143], v[80:81], off offset:-1024
	global_store_dwordx2 v[142:143], v[64:65], off offset:-512
	global_store_dwordx2 v[142:143], v[48:49], off
	global_store_dwordx2 v[142:143], v[32:33], off offset:512
	global_store_dwordx2 v[142:143], v[16:17], off offset:1024
	global_store_dwordx2 v[142:143], v[0:1], off offset:1536
	v_lshl_add_u64 v[142:143], v[142:143], 0, s[8:9]
	s_or_b64 s[4:5], vcc, s[4:5]
	s_andn2_b64 exec, exec, s[4:5]
	s_cbranch_execnz .LBB0_391
